# baseline (speedup 1.0000x reference)
; __device__ __forceinline__ int otid() { int t = threadIdx.x; asm volatile("" : "+v"(t)); return t; }
; __device__ __forceinline__ f32x16 mfma32(bf16x8 a, bf16x8 b, f32x16 c) { return __builtin_amdgcn_mfma_f32_32x32x16_bf16(a, b, c, 0, 0, 0); }
; __device__ void sb_task(const Params& p, int head, int qb128, char* smem) {
;   const int tid = otid() & 255, lane = tid & 63, w = tid >> 6, r = lane & 31, hf = lane >> 5;
;   const int q0 = qb128 * 128 + w * 32;
;   u16* vt = (u16*)smem + w * (32 * 72);
;   const u16* H = p.H;
;   bf16x8 qf[4];
; #pragma unroll
;   for (int s = 0; s < 4; ++s) qf[s] = *(const bf16x8*)(H + (long)(q0 + r) * INC + head * 64 + 16 * s + 8 * hf);
;   f32x16 o[2];
; #pragma unroll
;   for (int i = 0; i < 16; ++i) { o[0][i] = 0.f; o[1][i] = 0.f; }
;   float R = 0.f;
;   const int ktd = q0 / 32;
;   bf16x8 kfn[4]; u32x4 vrn[4];
; #pragma unroll
;   for (int s = 0; s < 4; ++s) kfn[s] = *(const bf16x8*)(H + (long)(ktd * 32 + r) * INC + 512 + head * 64 + 16 * s + 8 * hf);
; #pragma unroll
;   for (int i = 0; i < 4; ++i) { int id = lane + 64 * i, row = id >> 3, cc = id & 7; vrn[i] = *(const u32x4*)(H + (long)(ktd * 32 + row) * INC + 1024 + head * 64 + cc * 8); }
;     ...
;     const int k0 = kt * 32;
;     bf16x8 kfc[4]; u32x4 vrc[4];
; #pragma unroll
;     for (int s = 0; s < 4; ++s) { kfc[s] = kfn[s]; vrc[s] = vrn[s]; }
;     {
;       const int kp = (kt > 0 ? kt - 1 : 0) * 32;
;       __builtin_amdgcn_s_setprio(2);
; #pragma unroll
;       for (int s = 0; s < 4; ++s) kfn[s] = *(const bf16x8*)(H + (long)(kp + r) * INC + 512 + head * 64 + 16 * s + 8 * hf);
; #pragma unroll
;       for (int i = 0; i < 4; ++i) { int id = lane + 64 * i, row = id >> 3, cc = id & 7; vrn[i] = *(const u32x4*)(H + (long)(kp + row) * INC + 1024 + head * 64 + cc * 8); }
;       __builtin_amdgcn_s_setprio(0);
;     }
;     f32x16 z;
; #pragma unroll
;     for (int i = 0; i < 16; ++i) z[i] = 0.f;
; #pragma unroll
;     for (int s = 0; s < 4; ++s) z = mfma32(kfc[s], qf[s], z);
; #pragma unroll
;     for (int i = 0; i < 4; ++i) {
;       int id = lane + 64 * i, row = id >> 3, cc = id & 7;
;       *(u32x4*)(vt + row * 72 + cc * 8) = vrc[i];
.LBB0_892:
	v_mov_b32_e32 v32, v207
	v_lshlrev_b32_e32 v0, 4, v123
	v_and_b32_e32 v0, 0xffffff80, v0
	v_bfe_u32 v33, v32, 6, 2
	v_lshl_or_b32 v66, v33, 5, v0
	v_bfe_u32 v67, v32, 5, 1
	v_ashrrev_i32_e32 v125, 5, v66
	v_cmp_gt_i32_e32 vcc, 0, v125
	v_lshlrev_b32_e32 v112, 2, v67
	s_and_saveexec_b64 s[0:1], vcc
	s_xor_b64 s[0:1], exec, s[0:1]
	v_lshlrev_b32_e32 v112, 2, v67
	s_or_saveexec_b64 s[86:87], s[0:1]
	v_and_b32_e32 v80, 31, v32
	v_lshlrev_b32_e32 v0, 6, v123
	v_or_b32_e32 v114, v66, v80
	v_and_b32_e32 v0, 0x1c0, v0
	v_ashrrev_i32_e32 v115, 31, v114
	v_mov_b32_e32 v15, 0
	v_lshlrev_b32_e32 v176, 1, v0
	v_mov_b32_e32 v14, 0
	v_mov_b32_e32 v13, 0
	v_mov_b32_e32 v12, 0
	v_mov_b32_e32 v11, 0
	v_mov_b32_e32 v10, 0
	v_mov_b32_e32 v9, 0
	v_mov_b32_e32 v8, 0
	v_mov_b32_e32 v7, 0
	v_mov_b32_e32 v6, 0
	v_mov_b32_e32 v5, 0
	v_mov_b32_e32 v4, 0
	v_mov_b32_e32 v3, 0
	v_mov_b32_e32 v2, 0
	v_mov_b32_e32 v1, 0
	v_mov_b32_e32 v0, 0
	v_mov_b32_e32 v31, 0
	v_mov_b32_e32 v30, 0
	v_mov_b32_e32 v29, 0
	v_mov_b32_e32 v28, 0
	v_mov_b32_e32 v27, 0
	v_mov_b32_e32 v26, 0
	v_mov_b32_e32 v25, 0
	v_mov_b32_e32 v24, 0
	v_mov_b32_e32 v23, 0
	v_mov_b32_e32 v22, 0
	v_mov_b32_e32 v21, 0
	v_mov_b32_e32 v20, 0
	v_mov_b32_e32 v19, 0
	v_mov_b32_e32 v18, 0
	v_mov_b32_e32 v17, 0
	v_mov_b32_e32 v16, 0
	s_xor_b64 exec, exec, s[86:87]
	s_cbranch_execz .LBB0_891
	s_waitcnt vmcnt(10)
	v_and_b32_e32 v38, 63, v32
	v_lshlrev_b32_e32 v0, 3, v32
	v_lshrrev_b32_e32 v81, 3, v38
	v_and_b32_e32 v2, 56, v0
	v_or_b32_e32 v39, 8, v81
	s_waitcnt vmcnt(8)
	v_or_b32_e32 v42, 16, v81
	v_or_b32_e32 v44, 24, v81
	v_or_b32_e32 v0, v66, v44
	v_mov_b64_e32 v[40:41], s[56:57]
	v_lshlrev_b32_e32 v64, 1, v2
	v_or_b32_e32 v2, v66, v42
	v_or_b32_e32 v8, v66, v39
	v_or_b32_e32 v10, v66, v81
	v_mad_u64_u32 v[0:1], s[0:1], v0, s15, v[40:41]
	v_mad_u64_u32 v[2:3], s[0:1], v2, s15, v[40:41]
	v_mad_u64_u32 v[8:9], s[0:1], v8, s15, v[40:41]
	v_mad_u64_u32 v[10:11], s[0:1], v10, s15, v[40:41]
	v_mad_i64_i32 v[16:17], s[0:1], v114, s15, v[40:41]
	v_lshl_add_u64 v[0:1], v[0:1], 0, v[176:177]
	v_mov_b32_e32 v65, v177
	v_lshl_add_u64 v[2:3], v[2:3], 0, v[176:177]
	v_lshl_add_u64 v[8:9], v[8:9], 0, v[176:177]
	v_lshl_add_u64 v[10:11], v[10:11], 0, v[176:177]
	v_lshl_add_u64 v[16:17], v[16:17], 0, v[176:177]
	v_lshlrev_b32_e32 v34, 4, v67
	v_mov_b32_e32 v35, v177
	v_lshl_add_u64 v[0:1], v[0:1], 0, v[64:65]
	v_lshl_add_u64 v[4:5], v[2:3], 0, v[64:65]
	v_lshl_add_u64 v[8:9], v[8:9], 0, v[64:65]
	v_lshl_add_u64 v[12:13], v[10:11], 0, v[64:65]
	v_lshl_add_u64 v[36:37], v[16:17], 0, v[34:35]
	global_load_dwordx4 v[0:3], v[0:1], off offset:2048
	s_nop 0
	global_load_dwordx4 v[4:7], v[4:5], off offset:2048
	s_nop 0
	global_load_dwordx4 v[8:11], v[8:9], off offset:2048
	s_nop 0
	global_load_dwordx4 v[12:15], v[12:13], off offset:2048
	s_nop 0
	global_load_dwordx4 v[16:19], v[36:37], off offset:1120
	global_load_dwordx4 v[20:23], v[36:37], off offset:1088
	global_load_dwordx4 v[24:27], v[36:37], off offset:1056
	global_load_dwordx4 v[28:31], v[36:37], off offset:1024
	global_load_dwordx4 v[48:51], v[36:37], off offset:96
	global_load_dwordx4 v[52:55], v[36:37], off offset:64
	global_load_dwordx4 v[56:59], v[36:37], off offset:32
	global_load_dwordx4 v[60:63], v[36:37], off
	v_cmp_gt_u32_e32 vcc, 32, v38
	v_and_b32_e32 v36, 16, v32
	v_bfe_u32 v37, v32, 2, 2
	v_lshlrev_b32_e32 v38, 2, v38
	v_lshrrev_b32_e32 v32, 3, v32
	s_movk_i32 s0, 0x1200
	v_and_or_b32 v36, v38, 12, v36
	v_and_or_b32 v32, v32, 4, v37
	v_mad_u32_u24 v33, v33, s0, v120
	v_mul_u32_u24_e32 v32, 0x90, v32
	v_lshlrev_b32_e32 v36, 1, v36
	v_add3_u32 v113, v33, v32, v36
	v_sub_u32_e64 v32, v125, 1 clamp
	v_add_u32_e32 v82, v33, v64
	v_lshlrev_b32_e32 v45, 5, v32
	s_setprio 2
	v_or_b32_e32 v32, v45, v80
	v_mad_u64_u32 v[32:33], s[0:1], v32, s15, v[40:41]
	v_lshl_add_u64 v[32:33], v[32:33], 0, v[176:177]
	v_lshl_add_u64 v[36:37], v[32:33], 0, v[34:35]
	global_load_dwordx4 v[32:35], v[36:37], off offset:1024
	global_load_dwordx4 v[76:79], v[36:37], off offset:1056
	global_load_dwordx4 v[72:75], v[36:37], off offset:1088
	global_load_dwordx4 v[68:71], v[36:37], off offset:1120
	v_or_b32_e32 v36, v45, v81
	v_or_b32_e32 v38, v45, v39
	v_or_b32_e32 v42, v45, v42
	v_or_b32_e32 v44, v45, v44
	v_mad_u64_u32 v[36:37], s[0:1], v36, s15, v[40:41]
	v_mad_u64_u32 v[38:39], s[0:1], v38, s15, v[40:41]
	v_mad_u64_u32 v[42:43], s[0:1], v42, s15, v[40:41]
	v_mad_u64_u32 v[40:41], s[0:1], v44, s15, v[40:41]
	v_lshl_add_u64 v[36:37], v[36:37], 0, v[176:177]
	v_lshl_add_u64 v[38:39], v[38:39], 0, v[176:177]
	v_lshl_add_u64 v[42:43], v[42:43], 0, v[176:177]
	v_lshl_add_u64 v[40:41], v[40:41], 0, v[176:177]
	v_lshl_add_u64 v[36:37], v[36:37], 0, v[64:65]
	v_lshl_add_u64 v[38:39], v[38:39], 0, v[64:65]
	v_lshl_add_u64 v[42:43], v[42:43], 0, v[64:65]
	v_lshl_add_u64 v[40:41], v[40:41], 0, v[64:65]
	global_load_dwordx4 v[108:111], v[36:37], off offset:2048
	s_nop 0
	global_load_dwordx4 v[36:39], v[38:39], off offset:2048
	s_nop 0
	global_load_dwordx4 v[44:47], v[42:43], off offset:2048
	s_nop 0
	global_load_dwordx4 v[40:43], v[40:41], off offset:2048
	s_setprio 0
	s_movk_i32 s0, 0x90
	v_mad_u32_u24 v83, v81, s0, v82
	s_waitcnt vmcnt(16)
	ds_write_b128 v83, v[12:15]
	ds_write_b128 v83, v[8:11] offset:1152
	ds_write_b128 v83, v[4:7] offset:2304
	ds_write_b128 v83, v[0:3] offset:3456
	s_waitcnt vmcnt(8)
; __device__ __forceinline__ int krow(int i, int hf) { return (i & 3) + 8 * (i >> 2) + 4 * hf; }
; __device__ __forceinline__ f32x16 mfma32(bf16x8 a, bf16x8 b, f32x16 c) { return __builtin_amdgcn_mfma_f32_32x32x16_bf16(a, b, c, 0, 0, 0); }
; __device__ __forceinline__ float shx(float v, int m) { return __shfl_xor(v, m, 64); }
; __device__ void sb_task(const Params& p, int head, int qb128, char* smem) {
;     ...
;     for (int s = 0; s < 4; ++s) z = mfma32(kfc[s], qf[s], z);
; #pragma unroll
;     for (int i = 0; i < 4; ++i) {
;       int id = lane + 64 * i, row = id >> 3, cc = id & 7;
;       *(u32x4*)(vt + row * 72 + cc * 8) = vrc[i];
;     }
;     const bool diag = (kt == ktd);
;     float l1m[16], lb[16];
; #pragma unroll
;     for (int i = 0; i < 16; ++i) {
;       float zz = z[i] * 0.125f;
;       float t = __logf(1.f + __expf(-fabsf(zz)));
;       float lbv = fminf(zz, 0.f) - t;
;       bool valid = (!diag) || (krow(i, hf) < r);
;       lb[i] = valid ? lbv : -1e30f;
;       l1m[i] = valid ? (lbv - zz) : 0.f;
;     }
;     float Gs[4], Ps[4], after[4];
; #pragma unroll
;     for (int g = 0; g < 4; ++g) { Gs[g] = (l1m[4 * g] + l1m[4 * g + 1]) + (l1m[4 * g + 2] + l1m[4 * g + 3]); Ps[g] = shx(Gs[g], 32); }
	v_mfma_f32_32x32x16_bf16 v[0:15], v[28:31], v[60:63], 0
	v_mfma_f32_32x32x16_bf16 v[0:15], v[24:27], v[56:59], v[0:15]
	v_mfma_f32_32x32x16_bf16 v[0:15], v[20:23], v[52:55], v[0:15]
	v_mfma_f32_32x32x16_bf16 v[0:15], v[16:19], v[48:51], v[0:15]
	s_nop 11
	v_mul_f32_e32 v16, 0x3e000000, v0
	v_mul_f32_e64 v17, |v16|, s8
	v_exp_f32_e32 v17, v17
	v_min_f32_e32 v16, 0, v16
	v_mov_b32_e32 v20, v4
	v_mov_b32_e32 v21, v6
	v_add_f32_e32 v17, 1.0, v17
	v_pk_mul_f32 v[22:23], v[20:21], s[62:63] op_sel_hi:[1,0]
	v_mov_b32_e32 v6, v5
	v_log_f32_e32 v17, v17
	v_pk_mul_f32 v[4:5], v[6:7], s[62:63] op_sel_hi:[1,0]
	v_mul_f32_e32 v18, 0x3f317217, v17
	v_fma_f32 v18, v17, s71, -v18
	v_fmac_f32_e32 v18, 0x3377d1cf, v17
	v_fmac_f32_e32 v18, 0x3f317217, v17
	s_nop 1
	v_mov_b32_e32 v17, v18
	v_sub_f32_e32 v16, v16, v17
	v_cmp_lt_u32_e64 s[0:1], v112, v80
	s_nop 1
	v_cndmask_b32_e64 v24, v221, v16, s[0:1]
	v_fmac_f32_e32 v16, 0xbe000000, v0
	v_cndmask_b32_e64 v0, 0, v16, s[0:1]
	v_mul_f32_e32 v16, 0x3e000000, v1
	v_mul_f32_e64 v17, |v16|, s8
	v_exp_f32_e32 v17, v17
	v_min_f32_e32 v16, 0, v16
	v_add_f32_e32 v17, 1.0, v17
	s_nop 1
	v_log_f32_e32 v17, v17
	s_nop 0
	v_mul_f32_e32 v18, 0x3f317217, v17
	v_fma_f32 v18, v17, s71, -v18
	v_fmac_f32_e32 v18, 0x3377d1cf, v17
	v_fmac_f32_e32 v18, 0x3f317217, v17
	s_nop 1
	v_mov_b32_e32 v17, v18
	v_sub_f32_e32 v16, v16, v17
	v_or_b32_e32 v17, 1, v112
	v_cmp_lt_u32_e64 s[0:1], v17, v80
	s_nop 1
	v_cndmask_b32_e64 v25, v221, v16, s[0:1]
	v_fmac_f32_e32 v16, 0xbe000000, v1
	v_mul_f32_e32 v1, 0x3e000000, v2
	v_mul_f32_e64 v17, |v1|, s8
	v_exp_f32_e32 v17, v17
	v_cndmask_b32_e64 v16, 0, v16, s[0:1]
	v_min_f32_e32 v1, 0, v1
	v_add_f32_e32 v17, 1.0, v17
	s_nop 1
	v_log_f32_e32 v17, v17
	s_nop 0
	v_mul_f32_e32 v18, 0x3f317217, v17
	v_fma_f32 v18, v17, s71, -v18
	v_fmac_f32_e32 v18, 0x3377d1cf, v17
	v_fmac_f32_e32 v18, 0x3f317217, v17
	s_nop 1
	v_mov_b32_e32 v17, v18
	v_sub_f32_e32 v1, v1, v17
	v_or_b32_e32 v17, 2, v112
	v_cmp_lt_u32_e64 s[0:1], v17, v80
	s_nop 1
	v_cndmask_b32_e64 v26, v221, v1, s[0:1]
	v_fmac_f32_e32 v1, 0xbe000000, v2
	v_cndmask_b32_e64 v2, 0, v1, s[0:1]
	v_mul_f32_e32 v1, 0x3e000000, v3
	v_mul_f32_e64 v17, |v1|, s8
	v_exp_f32_e32 v17, v17
	v_min_f32_e32 v1, 0, v1
	v_add_f32_e32 v17, 1.0, v17
	s_nop 1
	v_log_f32_e32 v17, v17
	s_nop 0
	v_mul_f32_e32 v18, 0x3f317217, v17
	v_fma_f32 v18, v17, s71, -v18
	v_fmac_f32_e32 v18, 0x3377d1cf, v17
	v_fmac_f32_e32 v18, 0x3f317217, v17
	s_nop 1
	v_mov_b32_e32 v17, v18
	v_sub_f32_e32 v1, v1, v17
	v_or_b32_e32 v17, 3, v112
	v_cmp_lt_u32_e64 s[0:1], v17, v80
	s_nop 1
	v_cndmask_b32_e64 v27, v221, v1, s[0:1]
	v_fmac_f32_e32 v1, 0xbe000000, v3
	v_cndmask_b32_e64 v18, 0, v1, s[0:1]
	v_mul_f32_e64 v1, |v22|, s8
	v_exp_f32_e32 v1, v1
	v_min_f32_e32 v22, 0, v22
	v_add_f32_e32 v1, 1.0, v1
	s_nop 1
	v_log_f32_e32 v1, v1
	s_nop 0
	v_mul_f32_e32 v3, 0x3f317217, v1
	v_fma_f32 v3, v1, s71, -v3
	v_fmac_f32_e32 v3, 0x3377d1cf, v1
	v_fmac_f32_e32 v3, 0x3f317217, v1
	s_nop 1
	v_mov_b32_e32 v1, v3
	v_mov_b32_e32 v28, v1
	v_mul_f32_e64 v1, |v23|, s8
	v_exp_f32_e32 v1, v1
	v_min_f32_e32 v23, 0, v23
	v_add_f32_e32 v1, 1.0, v1
	s_nop 1
	v_log_f32_e32 v1, v1
	s_nop 0
	v_mul_f32_e32 v3, 0x3f317217, v1
	v_fma_f32 v3, v1, s71, -v3
	v_fmac_f32_e32 v3, 0x3377d1cf, v1
	v_fmac_f32_e32 v3, 0x3f317217, v1
	s_nop 1
	v_mov_b32_e32 v1, v3
	v_mov_b32_e32 v29, v1
	v_or_b32_e32 v1, 10, v112
	v_cmp_lt_u32_e64 s[0:1], v1, v80
	v_mul_f32_e64 v1, |v4|, s8
	v_exp_f32_e32 v1, v1
	v_or_b32_e32 v3, 8, v112
	v_cmp_lt_u32_e64 s[2:3], v3, v80
	v_pk_add_f32 v[22:23], v[22:23], v[28:29] neg_lo:[0,1] neg_hi:[0,1]
	v_add_f32_e32 v1, 1.0, v1
	v_min_f32_e32 v4, 0, v4
	v_cndmask_b32_e64 v28, v221, v22, s[2:3]
	v_log_f32_e32 v1, v1
	s_nop 0
	v_mul_f32_e32 v3, 0x3f317217, v1
	v_fma_f32 v3, v1, s71, -v3
	v_fmac_f32_e32 v3, 0x3377d1cf, v1
	v_fmac_f32_e32 v3, 0x3f317217, v1
	s_nop 1
	v_mov_b32_e32 v1, v3
	v_mov_b32_e32 v30, v1
	v_mul_f32_e64 v1, |v5|, s8
	v_exp_f32_e32 v1, v1
	v_min_f32_e32 v5, 0, v5
	v_add_f32_e32 v1, 1.0, v1
	s_nop 1
	v_log_f32_e32 v1, v1
	s_nop 0
	v_mul_f32_e32 v3, 0x3f317217, v1
	v_fma_f32 v3, v1, s71, -v3
	v_fmac_f32_e32 v3, 0x3377d1cf, v1
	v_fmac_f32_e32 v3, 0x3f317217, v1
	s_nop 1
	v_mov_b32_e32 v1, v3
	v_mov_b32_e32 v31, v1
	v_or_b32_e32 v1, 11, v112
	v_or_b32_e32 v3, 9, v112
	v_pk_add_f32 v[84:85], v[4:5], v[30:31] neg_lo:[0,1] neg_hi:[0,1]
	v_cmp_lt_u32_e64 s[38:39], v1, v80
	v_cmp_lt_u32_e64 s[40:41], v3, v80
	v_cndmask_b32_e64 v30, v221, v23, s[0:1]
	v_pk_fma_f32 v[4:5], v[20:21], s[62:63], v[22:23] op_sel_hi:[1,0,1] neg_lo:[1,0,0] neg_hi:[1,0,0]
	v_mov_b32_e32 v22, v8
	v_mov_b32_e32 v23, v10
	v_cndmask_b32_e64 v29, v221, v84, s[40:41]
	v_cndmask_b32_e64 v31, v221, v85, s[38:39]
	v_pk_fma_f32 v[6:7], v[6:7], s[62:63], v[84:85] op_sel_hi:[1,0,1] neg_lo:[1,0,0] neg_hi:[1,0,0]
	v_pk_mul_f32 v[84:85], v[22:23], s[62:63] op_sel_hi:[1,0]
	v_cndmask_b32_e64 v5, 0, v5, s[0:1]
	v_mul_f32_e64 v1, |v84|, s8
	v_exp_f32_e32 v1, v1
	v_cndmask_b32_e64 v4, 0, v4, s[2:3]
	v_mov_b32_e32 v10, v9
	v_pk_mul_f32 v[8:9], v[10:11], s[62:63] op_sel_hi:[1,0]
	v_add_f32_e32 v1, 1.0, v1
	v_cndmask_b32_e64 v7, 0, v7, s[38:39]
	v_cndmask_b32_e64 v6, 0, v6, s[40:41]
	v_log_f32_e32 v1, v1
	v_min_f32_e32 v84, 0, v84
	v_pk_add_f32 v[20:21], v[4:5], v[6:7]
	v_mul_f32_e32 v3, 0x3f317217, v1
	v_fma_f32 v3, v1, s71, -v3
	v_fmac_f32_e32 v3, 0x3377d1cf, v1
	v_fmac_f32_e32 v3, 0x3f317217, v1
	v_pk_add_f32 v[20:21], v[20:21], v[20:21] op_sel:[0,1] op_sel_hi:[1,0]
	ds_bpermute_b32 v17, v124, v20
	v_mov_b32_e32 v1, v3
	v_mov_b32_e32 v86, v1
	v_mul_f32_e64 v1, |v85|, s8
	v_exp_f32_e32 v1, v1
	v_min_f32_e32 v85, 0, v85
	s_waitcnt lgkmcnt(0)
; __device__ __forceinline__ int krow(int i, int hf) { return (i & 3) + 8 * (i >> 2) + 4 * hf; }
; __device__ __forceinline__ float shx(float v, int m) { return __shfl_xor(v, m, 64); }
; __device__ void sb_task(const Params& p, int head, int qb128, char* smem) {
;     ...
;     for (int i = 0; i < 16; ++i) {
;       float zz = z[i] * 0.125f;
;       float t = __logf(1.f + __expf(-fabsf(zz)));
;       float lbv = fminf(zz, 0.f) - t;
;       bool valid = (!diag) || (krow(i, hf) < r);
;       lb[i] = valid ? lbv : -1e30f;
;       l1m[i] = valid ? (lbv - zz) : 0.f;
;     }
;     float Gs[4], Ps[4], after[4];
; #pragma unroll
;     for (int g = 0; g < 4; ++g) { Gs[g] = (l1m[4 * g] + l1m[4 * g + 1]) + (l1m[4 * g + 2] + l1m[4 * g + 3]); Ps[g] = shx(Gs[g], 32); }
;     float run = 0.f;
; #pragma unroll
;     for (int g = 3; g >= 0; --g) { after[g] = run + (hf == 0 ? Ps[g] : 0.f); run += Gs[g] + Ps[g]; }
	v_cndmask_b32_e32 v89, 0, v17, vcc
	v_add_f32_e32 v1, 1.0, v1
	s_nop 1
	v_log_f32_e32 v1, v1
	s_nop 0
	v_mul_f32_e32 v3, 0x3f317217, v1
	v_fma_f32 v3, v1, s71, -v3
	v_fmac_f32_e32 v3, 0x3377d1cf, v1
	v_fmac_f32_e32 v3, 0x3f317217, v1
	s_nop 1
	v_mov_b32_e32 v1, v3
	v_mov_b32_e32 v87, v1
	v_or_b32_e32 v1, 18, v112
	v_cmp_lt_u32_e64 s[0:1], v1, v80
	v_mul_f32_e64 v1, |v8|, s8
	v_exp_f32_e32 v1, v1
	v_or_b32_e32 v3, 16, v112
	v_cmp_lt_u32_e64 s[2:3], v3, v80
	v_pk_add_f32 v[84:85], v[84:85], v[86:87] neg_lo:[0,1] neg_hi:[0,1]
	v_add_f32_e32 v1, 1.0, v1
	v_min_f32_e32 v8, 0, v8
	v_pk_fma_f32 v[22:23], v[22:23], s[62:63], v[84:85] op_sel_hi:[1,0,1] neg_lo:[1,0,0] neg_hi:[1,0,0]
	v_log_f32_e32 v1, v1
	v_cndmask_b32_e64 v23, 0, v23, s[0:1]
	v_cndmask_b32_e64 v22, 0, v22, s[2:3]
	v_cndmask_b32_e64 v4, v221, v84, s[2:3]
	v_mul_f32_e32 v3, 0x3f317217, v1
	v_fma_f32 v3, v1, s71, -v3
	v_fmac_f32_e32 v3, 0x3377d1cf, v1
	v_fmac_f32_e32 v3, 0x3f317217, v1
	v_cndmask_b32_e64 v83, v221, v85, s[0:1]
	s_nop 0
	v_mov_b32_e32 v1, v3
	v_mov_b32_e32 v86, v1
	v_mul_f32_e64 v1, |v9|, s8
	v_exp_f32_e32 v1, v1
	v_min_f32_e32 v9, 0, v9
	v_add_f32_e32 v1, 1.0, v1
	s_nop 1
	v_log_f32_e32 v1, v1
	s_nop 0
	v_mul_f32_e32 v3, 0x3f317217, v1
	v_fma_f32 v3, v1, s71, -v3
	v_fmac_f32_e32 v3, 0x3377d1cf, v1
	v_fmac_f32_e32 v3, 0x3f317217, v1
	s_nop 1
	v_mov_b32_e32 v1, v3
	v_mov_b32_e32 v87, v1
	v_or_b32_e32 v1, 19, v112
	v_or_b32_e32 v3, 17, v112
	v_pk_add_f32 v[8:9], v[8:9], v[86:87] neg_lo:[0,1] neg_hi:[0,1]
	v_cmp_lt_u32_e64 s[38:39], v1, v80
	v_cmp_lt_u32_e64 s[40:41], v3, v80
	s_nop 0
	v_cndmask_b32_e64 v88, v221, v9, s[38:39]
	v_cndmask_b32_e64 v21, v221, v8, s[40:41]
	v_pk_fma_f32 v[8:9], v[10:11], s[62:63], v[8:9] op_sel_hi:[1,0,1] neg_lo:[1,0,0] neg_hi:[1,0,0]
	s_nop 0
	v_cndmask_b32_e64 v9, 0, v9, s[38:39]
	v_cndmask_b32_e64 v8, 0, v8, s[40:41]
	v_pk_add_f32 v[10:11], v[22:23], v[8:9]
	s_nop 0
	v_add_f32_e32 v1, v10, v11
	v_mov_b32_e32 v10, v12
	v_mov_b32_e32 v11, v14
	v_pk_mul_f32 v[84:85], v[10:11], s[62:63] op_sel_hi:[1,0]
	ds_bpermute_b32 v3, v124, v1
	v_mul_f32_e64 v12, |v84|, s8
	v_exp_f32_e32 v12, v12
	v_min_f32_e32 v84, 0, v84
	v_add_f32_e32 v12, 1.0, v12
	s_nop 1
	v_log_f32_e32 v12, v12
	s_nop 0
	v_mul_f32_e32 v14, 0x3f317217, v12
	v_fma_f32 v14, v12, s71, -v14
	v_fmac_f32_e32 v14, 0x3377d1cf, v12
	v_fmac_f32_e32 v14, 0x3f317217, v12
	s_nop 1
	v_mov_b32_e32 v12, v14
	v_mov_b32_e32 v86, v12
	v_mul_f32_e64 v12, |v85|, s8
	v_exp_f32_e32 v12, v12
	v_min_f32_e32 v85, 0, v85
	v_add_f32_e32 v12, 1.0, v12
	s_nop 1
	v_log_f32_e32 v12, v12
	s_nop 0
	v_mul_f32_e32 v14, 0x3f317217, v12
	v_fma_f32 v14, v12, s71, -v14
	v_fmac_f32_e32 v14, 0x3377d1cf, v12
	v_fmac_f32_e32 v14, 0x3f317217, v12
	s_nop 1
	v_mov_b32_e32 v12, v14
	v_mov_b32_e32 v87, v12
	v_or_b32_e32 v14, 24, v112
	v_or_b32_e32 v12, 26, v112
	v_cmp_lt_u32_e64 s[2:3], v14, v80
	v_mov_b32_e32 v14, v13
	v_cmp_lt_u32_e64 s[0:1], v12, v80
	v_pk_mul_f32 v[12:13], v[14:15], s[62:63] op_sel_hi:[1,0]
	v_pk_add_f32 v[84:85], v[84:85], v[86:87] neg_lo:[0,1] neg_hi:[0,1]
	v_mul_f32_e64 v19, |v12|, s8
	v_exp_f32_e32 v19, v19
	v_min_f32_e32 v12, 0, v12
	v_cndmask_b32_e64 v22, v221, v84, s[2:3]
	v_pk_fma_f32 v[10:11], v[10:11], s[62:63], v[84:85] op_sel_hi:[1,0,1] neg_lo:[1,0,0] neg_hi:[1,0,0]
	v_add_f32_e32 v19, 1.0, v19
	v_cndmask_b32_e64 v11, 0, v11, s[0:1]
	v_cndmask_b32_e64 v10, 0, v10, s[2:3]
	v_log_f32_e32 v19, v19
	s_nop 0
	v_mul_f32_e32 v86, 0x3f317217, v19
	v_fma_f32 v86, v19, s71, -v86
	v_fmac_f32_e32 v86, 0x3377d1cf, v19
	v_fmac_f32_e32 v86, 0x3f317217, v19
	s_nop 1
	v_mov_b32_e32 v19, v86
	v_mov_b32_e32 v86, v19
	v_mul_f32_e64 v19, |v13|, s8
	v_exp_f32_e32 v19, v19
	v_min_f32_e32 v13, 0, v13
	v_add_f32_e32 v19, 1.0, v19
	s_nop 1
	v_log_f32_e32 v19, v19
	s_nop 0
	v_mul_f32_e32 v87, 0x3f317217, v19
	v_fma_f32 v87, v19, s71, -v87
	v_fmac_f32_e32 v87, 0x3377d1cf, v19
	v_fmac_f32_e32 v87, 0x3f317217, v19
	s_nop 1
	v_mov_b32_e32 v19, v87
	v_mov_b32_e32 v87, v19
	v_pk_add_f32 v[12:13], v[12:13], v[86:87] neg_lo:[0,1] neg_hi:[0,1]
	v_or_b32_e32 v19, 27, v112
	v_or_b32_e32 v86, 25, v112
	v_cmp_lt_u32_e64 s[38:39], v19, v80
	v_cmp_lt_u32_e64 s[40:41], v86, v80
	v_cndmask_b32_e64 v87, v221, v85, s[0:1]
	v_cndmask_b32_e64 v84, v221, v13, s[38:39]
	v_cndmask_b32_e64 v86, v221, v12, s[40:41]
	v_pk_fma_f32 v[12:13], v[14:15], s[62:63], v[12:13] op_sel_hi:[1,0,1] neg_lo:[1,0,0] neg_hi:[1,0,0]
	s_nop 0
	v_cndmask_b32_e64 v13, 0, v13, s[38:39]
	v_cndmask_b32_e64 v12, 0, v12, s[40:41]
	v_pk_add_f32 v[14:15], v[10:11], v[12:13]
	s_nop 0
	v_add_f32_e32 v10, v14, v15
	ds_bpermute_b32 v14, v124, v10
	s_waitcnt lgkmcnt(0)
	v_add_f32_e32 v10, v10, v14
	v_add_f32_e32 v15, 0, v14
	v_add_f32_e32 v19, 0, v10
	v_cndmask_b32_e32 v10, 0, v3, vcc
	v_add_f32_e32 v3, v1, v3
	v_mov_b32_e32 v1, v20
	v_cndmask_b32_e32 v85, 0, v15, vcc
	v_pk_add_f32 v[14:15], v[2:3], v[18:19]
	v_pk_add_f32 v[0:1], v[0:1], v[16:17]
	v_add_f32_e32 v10, v10, v19
	v_pk_add_f32 v[0:1], v[0:1], v[14:15]
	ds_bpermute_b32 v3, v124, v0
	v_add_f32_e32 v14, v89, v15
	v_add_f32_e32 v7, v7, v14
	v_add_f32_e32 v5, v5, v7
	v_add_f32_e32 v9, v9, v10
	s_waitcnt lgkmcnt(0)
; __device__ __forceinline__ f32x16 mfma32(bf16x8 a, bf16x8 b, f32x16 c) { return __builtin_amdgcn_mfma_f32_32x32x16_bf16(a, b, c, 0, 0, 0); }
; __device__ void sb_task(const Params& p, int head, int qb128, char* smem) {
;     ...
;     {
;       const int kp = (kt > 0 ? kt - 1 : 0) * 32;
;       __builtin_amdgcn_s_setprio(2);
; #pragma unroll
;       for (int s = 0; s < 4; ++s) kfn[s] = *(const bf16x8*)(H + (long)(kp + r) * INC + 512 + head * 64 + 16 * s + 8 * hf);
; #pragma unroll
;       for (int i = 0; i < 4; ++i) { int id = lane + 64 * i, row = id >> 3, cc = id & 7; vrn[i] = *(const u32x4*)(H + (long)(kp + row) * INC + 1024 + head * 64 + cc * 8); }
;       __builtin_amdgcn_s_setprio(0);
;     }
;     ...
;     float a[16];
; #pragma unroll
;     for (int g = 0; g < 4; ++g) {
;       float bt = R + after[g];
;       a[4 * g + 3] = __expf(lb[4 * g + 3] + bt); bt += l1m[4 * g + 3];
;       a[4 * g + 2] = __expf(lb[4 * g + 2] + bt); bt += l1m[4 * g + 2];
;       a[4 * g + 1] = __expf(lb[4 * g + 1] + bt); bt += l1m[4 * g + 1];
;       a[4 * g + 0] = __expf(lb[4 * g + 0] + bt);
;     }
;     R += run;
;     bf16x8 pb0 = pack8(a), pb1 = pack8(a + 8);
; #pragma unroll
;     for (int mb = 0; mb < 2; ++mb) {
;       bf16x8 A0 = tr_frag<true>(vt, 72, 0, mb * 32, lane);
;       bf16x8 A1 = tr_frag<true>(vt, 72, 16, mb * 32, lane);
;       o[mb] = mfma32(A0, pb0, o[mb]);
;       o[mb] = mfma32(A1, pb1, o[mb]);
;     }
;     if (__all(R < -104.f)) break;
	v_cndmask_b32_e32 v15, 0, v3, vcc
	v_add_f32_e32 v15, v15, v1
	v_add_f32_e32 v0, v0, v3
	v_add_f32_e32 v3, v27, v15
	v_add_f32_e32 v15, v18, v15
	v_add_f32_e32 v2, v2, v15
	v_add_f32_e32 v17, v26, v15
	v_add_f32_e32 v15, v25, v2
	v_add_f32_e32 v2, v16, v2
	v_add_f32_e32 v16, v31, v14
	v_add_f32_e32 v14, v30, v7
	v_add_f32_e32 v7, v29, v5
	v_add_f32_e32 v5, v6, v5
	v_add_f32_e32 v6, v88, v10
	v_add_f32_e32 v10, v83, v9
	v_add_f32_e32 v9, v23, v9
	v_add_f32_e32 v18, v21, v9
	v_add_f32_e32 v8, v8, v9
	v_add_f32_e32 v9, v85, v13
	v_add_f32_e32 v13, v87, v9
	v_add_f32_e32 v9, v11, v9
	v_add_f32_e32 v2, v24, v2
	v_add_f32_e32 v5, v28, v5
	v_add_f32_e32 v11, v86, v9
	v_add_f32_e32 v9, v12, v9
	v_mul_f32_e32 v3, 0x3fb8aa3b, v3
	v_mul_f32_e32 v17, 0x3fb8aa3b, v17
	v_mul_f32_e32 v15, 0x3fb8aa3b, v15
	v_mul_f32_e32 v2, 0x3fb8aa3b, v2
	v_mul_f32_e32 v16, 0x3fb8aa3b, v16
	v_mul_f32_e32 v14, 0x3fb8aa3b, v14
	v_mul_f32_e32 v7, 0x3fb8aa3b, v7
	v_mul_f32_e32 v5, 0x3fb8aa3b, v5
	v_add_f32_e32 v4, v4, v8
	v_add_f32_e32 v8, v85, v84
	v_add_f32_e32 v9, v22, v9
	v_exp_f32_e32 v3, v3
	v_exp_f32_e32 v17, v17
	v_exp_f32_e32 v15, v15
	v_exp_f32_e32 v2, v2
	v_exp_f32_e32 v16, v16
	v_exp_f32_e32 v14, v14
	v_exp_f32_e32 v7, v7
	v_exp_f32_e32 v5, v5
	v_mul_f32_e32 v6, 0x3fb8aa3b, v6
	v_mul_f32_e32 v18, 0x3fb8aa3b, v18
	v_mul_f32_e32 v4, 0x3fb8aa3b, v4
	v_mul_f32_e32 v8, 0x3fb8aa3b, v8
	v_mul_f32_e32 v13, 0x3fb8aa3b, v13
	v_mul_f32_e32 v11, 0x3fb8aa3b, v11
	v_mul_f32_e32 v9, 0x3fb8aa3b, v9
	v_exp_f32_e32 v6, v6
	v_exp_f32_e32 v18, v18
	v_exp_f32_e32 v4, v4
	v_exp_f32_e32 v8, v8
	v_exp_f32_e32 v13, v13
	v_exp_f32_e32 v11, v11
	v_exp_f32_e32 v9, v9
	v_mul_f32_e32 v10, 0x3fb8aa3b, v10
	v_exp_f32_e32 v10, v10
	v_add_f32_e32 v126, v0, v1
	v_bfe_u32 v0, v17, 16, 1
	v_bfe_u32 v1, v3, 16, 1
	v_bfe_u32 v12, v2, 16, 1
	v_bfe_u32 v19, v15, 16, 1
	v_bfe_u32 v20, v14, 16, 1
	v_bfe_u32 v21, v16, 16, 1
	v_bfe_u32 v22, v5, 16, 1
	v_bfe_u32 v23, v7, 16, 1
	v_add3_u32 v15, v15, v19, s65
	v_add3_u32 v2, v2, v12, s65
	v_add3_u32 v1, v3, v1, s65
	v_add3_u32 v0, v17, v0, s65
	v_add3_u32 v3, v7, v23, s65
	v_add3_u32 v5, v5, v22, s65
	v_add3_u32 v7, v16, v21, s65
	v_add3_u32 v12, v14, v20, s65
	v_bfe_u32 v16, v6, 16, 1
	v_bfe_u32 v17, v4, 16, 1
	v_bfe_u32 v19, v18, 16, 1
	v_bfe_u32 v20, v13, 16, 1
	v_bfe_u32 v21, v8, 16, 1
	v_bfe_u32 v22, v9, 16, 1
	v_bfe_u32 v23, v11, 16, 1
	v_add3_u32 v24, v18, v19, s65
	v_add3_u32 v4, v4, v17, s65
	v_add3_u32 v6, v6, v16, s65
	v_add3_u32 v11, v11, v23, s65
	v_add3_u32 v9, v9, v22, s65
	v_add3_u32 v8, v8, v21, s65
	v_add3_u32 v13, v13, v20, s65
	v_perm_b32 v17, v1, v0, s12
	v_perm_b32 v16, v15, v2, s12
	v_perm_b32 v18, v3, v5, s12
	ds_read_b64_tr_b16 v[0:1], v113
	ds_read_b64_tr_b16 v[2:3], v113 offset:1152
	ds_read_b64_tr_b16 v[20:21], v113 offset:2304
	ds_read_b64_tr_b16 v[22:23], v113 offset:3456
	v_bfe_u32 v14, v10, 16, 1
	v_add3_u32 v10, v10, v14, s65
	v_perm_b32 v19, v7, v12, s12
	v_perm_b32 v85, v6, v10, s12
	v_perm_b32 v84, v24, v4, s12
	v_perm_b32 v87, v8, v13, s12
	v_perm_b32 v86, v11, v9, s12
	s_waitcnt lgkmcnt(2)
	v_mfma_f32_32x32x16_bf16 v[0:15], v[0:3], v[16:19], 0
	v_cmp_gt_f32_e64 s[0:1], s13, v126
	s_cmp_lg_u64 s[0:1], exec
	s_cselect_b64 s[2:3], -1, 0
	v_cmp_ne_u32_e64 s[0:1], 0, v66
	s_and_b64 s[0:1], s[0:1], s[2:3]
	s_waitcnt lgkmcnt(0)
	v_mfma_f32_32x32x16_bf16 v[0:15], v[20:23], v[84:87], v[0:15]
	ds_read_b64_tr_b16 v[20:21], v113 offset:64
	ds_read_b64_tr_b16 v[22:23], v113 offset:1216
	ds_read_b64_tr_b16 v[88:89], v113 offset:2368
	ds_read_b64_tr_b16 v[90:91], v113 offset:3520
	s_waitcnt lgkmcnt(2)
	v_mfma_f32_32x32x16_bf16 v[16:31], v[20:23], v[16:19], 0
	s_waitcnt lgkmcnt(0)
	v_mfma_f32_32x32x16_bf16 v[16:31], v[88:91], v[84:87], v[16:31]
	s_and_saveexec_b64 s[38:39], s[0:1]
	s_cbranch_execz .LBB0_890
	v_lshlrev_b32_e32 v67, 3, v67
	v_mul_u32_u24_e32 v83, 0x90, v81
	v_lshl_add_u64 v[84:85], s[56:57], 0, v[176:177]
	v_lshlrev_b32_e32 v86, 1, v67
	v_mov_b32_e32 v87, v177
	s_movk_i32 s0, 0xffe0
	v_lshl_add_u64 v[116:117], v[84:85], 0, v[86:87]
	v_lshl_add_u64 v[118:119], v[84:85], 0, v[64:65]
	v_add_u32_e32 v127, v81, v66
	v_add_u32_e32 v128, -1, v125
	v_add3_u32 v129, v66, v80, s0
	s_mov_b64 s[40:41], 0
	v_add_u32_e32 v130, v82, v83
.LBB0_897:
	v_min_u32_e32 v64, 1, v128
	v_add_u32_e32 v131, -1, v125
	v_lshlrev_b32_e32 v66, 5, v64
	s_setprio 2
	v_sub_u32_e32 v64, v129, v66
	v_mad_u64_u32 v[64:65], s[0:1], v64, s15, v[116:117]
	v_sub_u32_e32 v90, v127, v66
	global_load_dwordx4 v[80:83], v[64:65], off offset:1024
	global_load_dwordx4 v[96:99], v[64:65], off offset:1056
	global_load_dwordx4 v[100:103], v[64:65], off offset:1088
	global_load_dwordx4 v[104:107], v[64:65], off offset:1120
	v_subrev_u32_e32 v64, 32, v90
	v_subrev_u32_e32 v66, 24, v90
	v_add_u32_e32 v88, -16, v90
	v_add_u32_e32 v90, -8, v90
	v_mad_u64_u32 v[64:65], s[0:1], v64, s15, v[118:119]
	v_mad_u64_u32 v[84:85], s[0:1], v66, s15, v[118:119]
	v_mad_u64_u32 v[88:89], s[0:1], v88, s15, v[118:119]
	v_mad_u64_u32 v[92:93], s[0:1], v90, s15, v[118:119]
	global_load_dwordx4 v[64:67], v[64:65], off offset:2048
	s_nop 0
	global_load_dwordx4 v[84:87], v[84:85], off offset:2048
	s_nop 0
	global_load_dwordx4 v[88:91], v[88:89], off offset:2048
	s_nop 0
	global_load_dwordx4 v[92:95], v[92:93], off offset:2048
	s_setprio 0
	s_waitcnt vmcnt(11)
	ds_write_b128 v130, v[108:111]
	s_waitcnt vmcnt(10)
	ds_write_b128 v130, v[36:39] offset:1152
	s_waitcnt vmcnt(9)
	ds_write_b128 v130, v[44:47] offset:2304
	s_waitcnt vmcnt(8)
; __device__ __forceinline__ int krow(int i, int hf) { return (i & 3) + 8 * (i >> 2) + 4 * hf; }
; __device__ __forceinline__ f32x16 mfma32(bf16x8 a, bf16x8 b, f32x16 c) { return __builtin_amdgcn_mfma_f32_32x32x16_bf16(a, b, c, 0, 0, 0); }
; __device__ void sb_task(const Params& p, int head, int qb128, char* smem) {
;     ...
;     f32x16 z;
; #pragma unroll
;     for (int i = 0; i < 16; ++i) z[i] = 0.f;
; #pragma unroll
;     for (int s = 0; s < 4; ++s) z = mfma32(kfc[s], qf[s], z);
; #pragma unroll
;     for (int i = 0; i < 4; ++i) {
;       int id = lane + 64 * i, row = id >> 3, cc = id & 7;
;       *(u32x4*)(vt + row * 72 + cc * 8) = vrc[i];
;     }
;     const bool diag = (kt == ktd);
;     float l1m[16], lb[16];
; #pragma unroll
;     for (int i = 0; i < 16; ++i) {
;       float zz = z[i] * 0.125f;
;       float t = __logf(1.f + __expf(-fabsf(zz)));
;       float lbv = fminf(zz, 0.f) - t;
;       bool valid = (!diag) || (krow(i, hf) < r);
;       lb[i] = valid ? lbv : -1e30f;
;       l1m[i] = valid ? (lbv - zz) : 0.f;
;     }
	ds_write_b128 v130, v[40:43] offset:3456
	v_mfma_f32_32x32x16_bf16 v[32:47], v[32:35], v[60:63], 0
	v_subrev_u32_e32 v127, 32, v127
	v_add_u32_e32 v128, -1, v128
	v_subrev_u32_e32 v129, 32, v129
	v_mfma_f32_32x32x16_bf16 v[32:47], v[76:79], v[56:59], v[32:47]
	v_mfma_f32_32x32x16_bf16 v[32:47], v[72:75], v[52:55], v[32:47]
	v_mfma_f32_32x32x16_bf16 v[32:47], v[68:71], v[48:51], v[32:47]
	s_nop 11
	v_mul_f32_e32 v68, 0x3e000000, v32
	v_mul_f32_e64 v32, |v68|, s8
	v_exp_f32_e32 v32, v32
	v_mul_f32_e32 v71, 0x3e000000, v33
	v_mul_f32_e64 v33, |v71|, s8
	v_exp_f32_e32 v33, v33
	v_add_f32_e32 v32, 1.0, v32
	v_pk_mul_f32 v[74:75], v[36:37], s[62:63] op_sel_hi:[1,0]
	v_add_f32_e32 v33, 1.0, v33
	v_log_f32_e32 v32, v32
	v_mov_b32_e32 v110, v40
	v_mov_b32_e32 v111, v42
	v_pk_mul_f32 v[132:133], v[110:111], s[62:63] op_sel_hi:[1,0]
	v_mul_f32_e32 v69, 0x3f317217, v32
	v_fma_f32 v69, v32, s71, -v69
	v_fmac_f32_e32 v69, 0x3377d1cf, v32
	v_fmac_f32_e32 v69, 0x3f317217, v32
	v_mov_b32_e32 v42, v41
	v_pk_mul_f32 v[134:135], v[42:43], s[62:63] op_sel_hi:[1,0]
	v_mov_b32_e32 v32, v69
	v_mov_b32_e32 v70, v32
	v_min_f32_e32 v32, 0, v68
	v_log_f32_e32 v33, v33
	s_nop 0
	v_mul_f32_e32 v69, 0x3f317217, v33
	v_fma_f32 v69, v33, s71, -v69
	v_fmac_f32_e32 v69, 0x3377d1cf, v33
	v_fmac_f32_e32 v69, 0x3f317217, v33
	s_nop 1
	v_mov_b32_e32 v33, v69
	v_min_f32_e32 v69, 0, v71
	v_sub_f32_e32 v33, v69, v33
	v_pk_add_f32 v[70:71], v[32:33], v[70:71] neg_lo:[0,1] neg_hi:[0,1]
	v_mul_f32_e32 v32, 0x3e000000, v34
	v_mul_f32_e64 v69, |v32|, s8
	v_exp_f32_e32 v69, v69
	v_min_f32_e32 v32, 0, v32
	v_add_f32_e32 v69, 1.0, v69
	s_nop 1
	v_log_f32_e32 v69, v69
	s_nop 0
	v_mul_f32_e32 v72, 0x3f317217, v69
	v_fma_f32 v72, v69, s71, -v72
	v_fmac_f32_e32 v72, 0x3377d1cf, v69
	v_fmac_f32_e32 v72, 0x3f317217, v69
	s_nop 1
	v_mov_b32_e32 v69, v72
	v_sub_f32_e32 v32, v32, v69
	v_mul_f32_e32 v69, 0x3e000000, v35
	v_mul_f32_e64 v72, |v69|, s8
	v_exp_f32_e32 v72, v72
	v_min_f32_e32 v69, 0, v69
	v_fmamk_f32 v34, v34, 0xbe000000, v32
	v_add_f32_e32 v72, 1.0, v72
	s_nop 1
	v_log_f32_e32 v72, v72
	s_nop 0
	v_mul_f32_e32 v73, 0x3f317217, v72
	v_fma_f32 v73, v72, s71, -v73
	v_fmac_f32_e32 v73, 0x3377d1cf, v72
	v_fmac_f32_e32 v73, 0x3f317217, v72
	s_nop 1
	v_mov_b32_e32 v72, v73
	v_sub_f32_e32 v142, v69, v72
	v_fmamk_f32 v72, v35, 0xbe000000, v142
	v_mul_f32_e64 v35, |v74|, s8
	v_exp_f32_e32 v35, v35
	v_min_f32_e32 v74, 0, v74
	v_add_f32_e32 v35, 1.0, v35
	s_nop 1
	v_log_f32_e32 v35, v35
	s_nop 0
	v_mul_f32_e32 v69, 0x3f317217, v35
	v_fma_f32 v69, v35, s71, -v69
	v_fmac_f32_e32 v69, 0x3377d1cf, v35
	v_fmac_f32_e32 v69, 0x3f317217, v35
	s_nop 1
	v_mov_b32_e32 v35, v69
	v_mov_b32_e32 v76, v35
	v_mul_f32_e64 v35, |v75|, s8
	v_exp_f32_e32 v35, v35
	v_min_f32_e32 v75, 0, v75
	v_add_f32_e32 v35, 1.0, v35
	s_nop 1
	v_log_f32_e32 v35, v35
	s_nop 0
	v_mul_f32_e32 v69, 0x3f317217, v35
	v_fma_f32 v69, v35, s71, -v69
	v_fmac_f32_e32 v69, 0x3377d1cf, v35
	v_fmac_f32_e32 v69, 0x3f317217, v35
	s_nop 1
	v_mov_b32_e32 v35, v69
	v_mov_b32_e32 v77, v35
	v_pk_add_f32 v[74:75], v[74:75], v[76:77] neg_lo:[0,1] neg_hi:[0,1]
	v_pk_mul_f32 v[76:77], v[38:39], s[62:63] op_sel_hi:[1,0]
	v_pk_fma_f32 v[36:37], v[36:37], s[62:63], v[74:75] op_sel_hi:[1,0,1] neg_lo:[1,0,0] neg_hi:[1,0,0]
	v_mul_f32_e64 v35, |v76|, s8
	v_exp_f32_e32 v35, v35
	v_min_f32_e32 v76, 0, v76
	v_add_f32_e32 v35, 1.0, v35
	s_nop 1
	v_log_f32_e32 v35, v35
	s_nop 0
	v_mul_f32_e32 v69, 0x3f317217, v35
	v_fma_f32 v69, v35, s71, -v69
	v_fmac_f32_e32 v69, 0x3377d1cf, v35
	v_fmac_f32_e32 v69, 0x3f317217, v35
	s_nop 1
	v_mov_b32_e32 v35, v69
	v_mov_b32_e32 v78, v35
	v_mul_f32_e64 v35, |v77|, s8
	v_exp_f32_e32 v35, v35
	v_min_f32_e32 v77, 0, v77
	v_add_f32_e32 v35, 1.0, v35
	s_nop 1
	v_log_f32_e32 v35, v35
	s_nop 0
	v_mul_f32_e32 v69, 0x3f317217, v35
	v_fma_f32 v69, v35, s71, -v69
	v_fmac_f32_e32 v69, 0x3377d1cf, v35
	v_fmac_f32_e32 v69, 0x3f317217, v35
	s_nop 1
	v_mov_b32_e32 v35, v69
	v_mov_b32_e32 v79, v35
	v_mul_f32_e64 v35, |v132|, s8
	v_exp_f32_e32 v35, v35
	v_pk_add_f32 v[76:77], v[76:77], v[78:79] neg_lo:[0,1] neg_hi:[0,1]
	v_pk_add_f32 v[78:79], v[36:37], v[36:37] op_sel_hi:[0,1]
	v_min_f32_e32 v132, 0, v132
	v_add_f32_e32 v35, 1.0, v35
	v_pk_fma_f32 v[38:39], v[38:39], s[62:63], v[76:77] op_sel_hi:[1,0,1] neg_lo:[1,0,0] neg_hi:[1,0,0]
	s_nop 0
	v_log_f32_e32 v35, v35
	v_pk_add_f32 v[108:109], v[38:39], v[38:39] op_sel_hi:[0,1]
	v_mul_f32_e32 v36, 0x3f317217, v35
	v_fma_f32 v36, v35, s71, -v36
	v_fmac_f32_e32 v36, 0x3377d1cf, v35
	v_fmac_f32_e32 v36, 0x3f317217, v35
	s_nop 1
	v_mov_b32_e32 v35, v36
	v_mov_b32_e32 v40, v35
	v_mul_f32_e64 v35, |v134|, s8
	v_exp_f32_e32 v35, v35
	v_min_f32_e32 v134, 0, v134
	v_add_f32_e32 v35, 1.0, v35
	s_nop 1
	v_log_f32_e32 v35, v35
	s_nop 0
	v_mul_f32_e32 v36, 0x3f317217, v35
	v_fma_f32 v36, v35, s71, -v36
	v_fmac_f32_e32 v36, 0x3377d1cf, v35
	v_fmac_f32_e32 v36, 0x3f317217, v35
	s_nop 1
	v_mov_b32_e32 v35, v36
	v_mov_b32_e32 v136, v35
	v_mul_f32_e64 v35, |v133|, s8
	v_exp_f32_e32 v35, v35
	v_min_f32_e32 v133, 0, v133
	v_add_f32_e32 v35, 1.0, v35
	s_nop 1
	v_log_f32_e32 v35, v35
	s_nop 0
	v_mul_f32_e32 v36, 0x3f317217, v35
	v_fma_f32 v36, v35, s71, -v36
	v_fmac_f32_e32 v36, 0x3377d1cf, v35
	v_fmac_f32_e32 v36, 0x3f317217, v35
	s_nop 1
	v_mov_b32_e32 v35, v36
	v_mov_b32_e32 v41, v35
	v_mul_f32_e64 v35, |v135|, s8
	v_exp_f32_e32 v35, v35
	v_min_f32_e32 v135, 0, v135
	v_pk_add_f32 v[40:41], v[132:133], v[40:41] neg_lo:[0,1] neg_hi:[0,1]
	v_add_f32_e32 v35, 1.0, v35
	v_pk_fma_f32 v[110:111], v[110:111], s[62:63], v[40:41] op_sel_hi:[1,0,1] neg_lo:[1,0,0] neg_hi:[1,0,0]
	s_nop 0
	v_log_f32_e32 v35, v35
	s_nop 0
	v_mul_f32_e32 v36, 0x3f317217, v35
	v_fma_f32 v36, v35, s71, -v36
	v_fmac_f32_e32 v36, 0x3377d1cf, v35
	v_fmac_f32_e32 v36, 0x3f317217, v35
	s_nop 1
	v_mov_b32_e32 v35, v36
	v_mov_b32_e32 v137, v35
	v_pk_add_f32 v[132:133], v[134:135], v[136:137] neg_lo:[0,1] neg_hi:[0,1]
	s_nop 0
	v_pk_fma_f32 v[42:43], v[42:43], s[62:63], v[132:133] op_sel_hi:[1,0,1] neg_lo:[1,0,0] neg_hi:[1,0,0]
	s_nop 0
	v_pk_add_f32 v[134:135], v[110:111], v[42:43]
	s_nop 0
	v_add_f32_e32 v35, v134, v135
	v_mov_b32_e32 v134, v44
	v_mov_b32_e32 v135, v46
	v_pk_mul_f32 v[136:137], v[134:135], s[62:63] op_sel_hi:[1,0]
	ds_bpermute_b32 v36, v124, v35
	v_mul_f32_e64 v44, |v136|, s8
	v_exp_f32_e32 v44, v44
	v_min_f32_e32 v136, 0, v136
	s_waitcnt lgkmcnt(0)
; __device__ __forceinline__ int krow(int i, int hf) { return (i & 3) + 8 * (i >> 2) + 4 * hf; }
; __device__ __forceinline__ float shx(float v, int m) { return __shfl_xor(v, m, 64); }
; __device__ void sb_task(const Params& p, int head, int qb128, char* smem) {
;     ...
;     for (int i = 0; i < 16; ++i) {
;       float zz = z[i] * 0.125f;
;       float t = __logf(1.f + __expf(-fabsf(zz)));
;       float lbv = fminf(zz, 0.f) - t;
;       bool valid = (!diag) || (krow(i, hf) < r);
;       lb[i] = valid ? lbv : -1e30f;
;       l1m[i] = valid ? (lbv - zz) : 0.f;
;     }
;     float Gs[4], Ps[4], after[4];
; #pragma unroll
;     for (int g = 0; g < 4; ++g) { Gs[g] = (l1m[4 * g] + l1m[4 * g + 1]) + (l1m[4 * g + 2] + l1m[4 * g + 3]); Ps[g] = shx(Gs[g], 32); }
;     float run = 0.f;
; #pragma unroll
;     for (int g = 3; g >= 0; --g) { after[g] = run + (hf == 0 ? Ps[g] : 0.f); run += Gs[g] + Ps[g]; }
	v_add_f32_e32 v35, v35, v36
	v_add_f32_e32 v44, 1.0, v44
	s_nop 1
	v_log_f32_e32 v44, v44
	s_nop 0
	v_mul_f32_e32 v46, 0x3f317217, v44
	v_fma_f32 v46, v44, s71, -v46
	v_fmac_f32_e32 v46, 0x3377d1cf, v44
	v_fmac_f32_e32 v46, 0x3f317217, v44
	s_nop 1
	v_mov_b32_e32 v44, v46
	v_mov_b32_e32 v46, v45
	v_pk_mul_f32 v[138:139], v[46:47], s[62:63] op_sel_hi:[1,0]
	s_nop 0
	v_mul_f32_e64 v45, |v138|, s8
	v_exp_f32_e32 v45, v45
	v_min_f32_e32 v138, 0, v138
	v_add_f32_e32 v45, 1.0, v45
	s_nop 1
	v_log_f32_e32 v45, v45
	s_nop 0
	v_mul_f32_e32 v69, 0x3f317217, v45
	v_fma_f32 v69, v45, s71, -v69
	v_fmac_f32_e32 v69, 0x3377d1cf, v45
	v_fmac_f32_e32 v69, 0x3f317217, v45
	s_nop 1
	v_mov_b32_e32 v45, v69
	v_mov_b32_e32 v140, v45
	v_mul_f32_e64 v45, |v137|, s8
	v_exp_f32_e32 v45, v45
	v_min_f32_e32 v137, 0, v137
	v_add_f32_e32 v45, 1.0, v45
	s_nop 1
	v_log_f32_e32 v45, v45
	s_nop 0
	v_mul_f32_e32 v69, 0x3f317217, v45
	v_fma_f32 v69, v45, s71, -v69
	v_fmac_f32_e32 v69, 0x3377d1cf, v45
	v_fmac_f32_e32 v69, 0x3f317217, v45
	s_nop 1
	v_mov_b32_e32 v45, v69
	v_mul_f32_e64 v69, |v139|, s8
	v_exp_f32_e32 v69, v69
	v_min_f32_e32 v139, 0, v139
	v_pk_add_f32 v[44:45], v[136:137], v[44:45] neg_lo:[0,1] neg_hi:[0,1]
	v_add_f32_e32 v69, 1.0, v69
	v_pk_fma_f32 v[134:135], v[134:135], s[62:63], v[44:45] op_sel_hi:[1,0,1] neg_lo:[1,0,0] neg_hi:[1,0,0]
	s_nop 0
	v_log_f32_e32 v69, v69
	s_nop 0
	v_mul_f32_e32 v73, 0x3f317217, v69
	v_fma_f32 v73, v69, s71, -v73
	v_fmac_f32_e32 v73, 0x3377d1cf, v69
	v_fmac_f32_e32 v73, 0x3f317217, v69
	s_nop 1
	v_mov_b32_e32 v69, v73
	v_mov_b32_e32 v141, v69
	v_pk_add_f32 v[136:137], v[138:139], v[140:141] neg_lo:[0,1] neg_hi:[0,1]
	s_nop 0
	v_pk_fma_f32 v[46:47], v[46:47], s[62:63], v[136:137] op_sel_hi:[1,0,1] neg_lo:[1,0,0] neg_hi:[1,0,0]
	s_nop 0
	v_pk_add_f32 v[138:139], v[134:135], v[46:47]
	s_nop 0
	v_add_f32_e32 v69, v138, v139
	ds_bpermute_b32 v73, v124, v69
	s_waitcnt lgkmcnt(0)
	v_add_f32_e32 v69, v69, v73
	v_add_f32_e32 v78, 0, v73
	v_add_f32_e32 v73, 0, v69
	v_cndmask_b32_e32 v69, 0, v36, vcc
	v_cndmask_b32_e32 v110, 0, v78, vcc
	v_add_f32_e32 v134, v69, v73
	v_mov_b32_e32 v78, v70
	v_mov_b32_e32 v69, v109
	v_pk_add_f32 v[108:109], v[70:71], v[68:69] neg_lo:[0,1] neg_hi:[0,1]
	v_pk_add_f32 v[68:69], v[78:79], v[68:69]
	v_pk_add_f32 v[78:79], v[34:35], v[72:73]
	v_mov_b32_e32 v109, v69
	ds_bpermute_b32 v69, v124, v69
	v_mov_b32_e32 v68, v71
	s_waitcnt lgkmcnt(0)
	v_pk_add_f32 v[108:109], v[108:109], v[68:69]
	s_nop 0
	v_pk_add_f32 v[108:109], v[108:109], v[78:79]
	ds_bpermute_b32 v35, v124, v108
	v_cndmask_b32_e32 v36, 0, v69, vcc
	v_add_f32_e32 v36, v36, v79
	v_add_f32_e32 v36, v126, v36
	s_waitcnt lgkmcnt(0)
; __device__ __forceinline__ f32x16 mfma32(bf16x8 a, bf16x8 b, f32x16 c) { return __builtin_amdgcn_mfma_f32_32x32x16_bf16(a, b, c, 0, 0, 0); }
; __device__ void sb_task(const Params& p, int head, int qb128, char* smem) {
;     ...
;     float a[16];
; #pragma unroll
;     for (int g = 0; g < 4; ++g) {
;       float bt = R + after[g];
;       a[4 * g + 3] = __expf(lb[4 * g + 3] + bt); bt += l1m[4 * g + 3];
;       a[4 * g + 2] = __expf(lb[4 * g + 2] + bt); bt += l1m[4 * g + 2];
;       a[4 * g + 1] = __expf(lb[4 * g + 1] + bt); bt += l1m[4 * g + 1];
;       a[4 * g + 0] = __expf(lb[4 * g + 0] + bt);
;     }
;     R += run;
;     bf16x8 pb0 = pack8(a), pb1 = pack8(a + 8);
; #pragma unroll
;     for (int mb = 0; mb < 2; ++mb) {
;       bf16x8 A0 = tr_frag<true>(vt, 72, 0, mb * 32, lane);
;       bf16x8 A1 = tr_frag<true>(vt, 72, 16, mb * 32, lane);
;       o[mb] = mfma32(A0, pb0, o[mb]);
;       o[mb] = mfma32(A1, pb1, o[mb]);
;     }
;     if (__all(R < -104.f)) break;
	v_cndmask_b32_e32 v68, 0, v35, vcc
	v_add_f32_e32 v68, v68, v109
	v_add_f32_e32 v68, v126, v68
	v_add_f32_e32 v69, v142, v68
	v_add_f32_e32 v68, v72, v68
	v_add_f32_e32 v32, v32, v68
	v_add_f32_e32 v34, v34, v68
	v_add_f32_e32 v68, v77, v36
	v_add_f32_e32 v36, v39, v36
	v_add_f32_e32 v39, v76, v36
	v_add_f32_e32 v36, v38, v36
	v_add_f32_e32 v33, v33, v34
	v_add_f32_e32 v34, v71, v34
	v_add_f32_e32 v38, v75, v36
	v_add_f32_e32 v36, v37, v36
	v_add_f32_e32 v37, v126, v134
	v_add_f32_e32 v34, v70, v34
	v_add_f32_e32 v70, v133, v37
	v_add_f32_e32 v37, v43, v37
	v_add_f32_e32 v41, v41, v37
	v_add_f32_e32 v37, v111, v37
	v_add_f32_e32 v43, v132, v37
	v_add_f32_e32 v37, v42, v37
	v_add_f32_e32 v37, v40, v37
	v_add_f32_e32 v40, v126, v110
	v_add_f32_e32 v42, v137, v40
	v_add_f32_e32 v40, v40, v47
	v_add_f32_e32 v45, v45, v40
	v_add_f32_e32 v40, v135, v40
	v_add_f32_e32 v36, v74, v36
	v_add_f32_e32 v47, v136, v40
	v_add_f32_e32 v40, v46, v40
	v_mul_f32_e32 v69, 0x3fb8aa3b, v69
	v_mul_f32_e32 v32, 0x3fb8aa3b, v32
	v_mul_f32_e32 v33, 0x3fb8aa3b, v33
	v_mul_f32_e32 v34, 0x3fb8aa3b, v34
	v_mul_f32_e32 v68, 0x3fb8aa3b, v68
	v_mul_f32_e32 v39, 0x3fb8aa3b, v39
	v_mul_f32_e32 v38, 0x3fb8aa3b, v38
	v_mul_f32_e32 v36, 0x3fb8aa3b, v36
	v_add_f32_e32 v40, v44, v40
	v_exp_f32_e32 v69, v69
	v_exp_f32_e32 v32, v32
	v_exp_f32_e32 v33, v33
	v_exp_f32_e32 v34, v34
	v_exp_f32_e32 v68, v68
	v_exp_f32_e32 v39, v39
	v_exp_f32_e32 v38, v38
	v_exp_f32_e32 v36, v36
	v_mul_f32_e32 v70, 0x3fb8aa3b, v70
	v_mul_f32_e32 v41, 0x3fb8aa3b, v41
	v_mul_f32_e32 v43, 0x3fb8aa3b, v43
	v_mul_f32_e32 v37, 0x3fb8aa3b, v37
	v_mul_f32_e32 v42, 0x3fb8aa3b, v42
	v_mul_f32_e32 v45, 0x3fb8aa3b, v45
	v_mul_f32_e32 v47, 0x3fb8aa3b, v47
	v_mul_f32_e32 v40, 0x3fb8aa3b, v40
	v_exp_f32_e32 v70, v70
	v_exp_f32_e32 v41, v41
	v_exp_f32_e32 v43, v43
	v_exp_f32_e32 v37, v37
	v_exp_f32_e32 v42, v42
	v_exp_f32_e32 v45, v45
	v_exp_f32_e32 v47, v47
	v_exp_f32_e32 v40, v40
	v_add_f32_e32 v35, v108, v35
	v_add_f32_e32 v71, v35, v109
	v_bfe_u32 v35, v32, 16, 1
	v_bfe_u32 v44, v69, 16, 1
	v_bfe_u32 v46, v34, 16, 1
	v_bfe_u32 v72, v33, 16, 1
	v_bfe_u32 v73, v39, 16, 1
	v_bfe_u32 v74, v68, 16, 1
	v_bfe_u32 v75, v36, 16, 1
	v_bfe_u32 v76, v38, 16, 1
	v_add3_u32 v72, v33, v72, s65
	v_add3_u32 v34, v34, v46, s65
	v_add3_u32 v33, v69, v44, s65
	v_add3_u32 v32, v32, v35, s65
	v_add3_u32 v38, v38, v76, s65
	v_add3_u32 v36, v36, v75, s65
	v_add3_u32 v35, v68, v74, s65
	v_add3_u32 v39, v39, v73, s65
	v_bfe_u32 v44, v41, 16, 1
	v_bfe_u32 v46, v70, 16, 1
	v_bfe_u32 v68, v37, 16, 1
	v_bfe_u32 v69, v43, 16, 1
	v_bfe_u32 v73, v45, 16, 1
	v_bfe_u32 v74, v42, 16, 1
	v_bfe_u32 v75, v40, 16, 1
	v_bfe_u32 v76, v47, 16, 1
	v_add3_u32 v43, v43, v69, s65
	v_add3_u32 v68, v37, v68, s65
	v_add3_u32 v37, v70, v46, s65
	v_add3_u32 v41, v41, v44, s65
	v_add3_u32 v44, v47, v76, s65
	v_add3_u32 v40, v40, v75, s65
	v_add3_u32 v42, v42, v74, s65
	v_add3_u32 v45, v45, v73, s65
	v_perm_b32 v33, v33, v32, s12
	v_perm_b32 v32, v72, v34, s12
	v_perm_b32 v35, v35, v39, s12
	v_perm_b32 v34, v38, v36, s12
	v_perm_b32 v37, v37, v41, s12
	v_perm_b32 v36, v43, v68, s12
	v_perm_b32 v39, v42, v45, s12
	v_perm_b32 v38, v44, v40, s12
	ds_read_b64_tr_b16 v[40:41], v113
	ds_read_b64_tr_b16 v[42:43], v113 offset:1152
	ds_read_b64_tr_b16 v[44:45], v113 offset:2304
	ds_read_b64_tr_b16 v[46:47], v113 offset:3456
	s_waitcnt lgkmcnt(2)
	v_mfma_f32_32x32x16_bf16 v[0:15], v[40:43], v[32:35], v[0:15]
	v_add_f32_e32 v126, v126, v71
	v_cmp_gt_f32_e64 s[0:1], s13, v126
	s_cmp_eq_u64 s[0:1], exec
	s_cselect_b64 s[2:3], -1, 0
	v_cmp_gt_u32_e64 s[0:1], 2, v125
	s_or_b64 s[0:1], s[2:3], s[0:1]
	s_and_b64 s[0:1], exec, s[0:1]
	s_waitcnt lgkmcnt(0)
	v_mfma_f32_32x32x16_bf16 v[0:15], v[44:47], v[36:39], v[0:15]
	ds_read_b64_tr_b16 v[40:41], v113 offset:64
	ds_read_b64_tr_b16 v[42:43], v113 offset:1216
	ds_read_b64_tr_b16 v[44:45], v113 offset:2368
	ds_read_b64_tr_b16 v[46:47], v113 offset:3520
	s_waitcnt vmcnt(4)
	v_mov_b64_e32 v[68:69], v[104:105]
	v_mov_b64_e32 v[72:73], v[100:101]
	v_mov_b64_e32 v[76:77], v[96:97]
	s_waitcnt vmcnt(3)
	v_mov_b64_e32 v[110:111], v[66:67]
	s_or_b64 s[40:41], s[0:1], s[40:41]
	v_mov_b64_e32 v[70:71], v[106:107]
	s_waitcnt lgkmcnt(2)
	v_mfma_f32_32x32x16_bf16 v[16:31], v[40:43], v[32:35], v[16:31]
	v_mov_b64_e32 v[32:33], v[80:81]
	s_waitcnt vmcnt(0)
	v_mov_b64_e32 v[40:41], v[92:93]
	v_mov_b64_e32 v[74:75], v[102:103]
	v_mov_b64_e32 v[78:79], v[98:99]
	v_mov_b64_e32 v[34:35], v[82:83]
	v_mov_b64_e32 v[42:43], v[94:95]
	v_mov_b64_e32 v[108:109], v[64:65]
	s_waitcnt lgkmcnt(0)
	v_mfma_f32_32x32x16_bf16 v[16:31], v[44:47], v[36:39], v[16:31]
	v_mov_b64_e32 v[44:45], v[88:89]
	v_mov_b64_e32 v[36:37], v[84:85]
	v_mov_b64_e32 v[46:47], v[90:91]
	v_mov_b64_e32 v[38:39], v[86:87]
	v_mov_b32_e32 v125, v131
	s_andn2_b64 exec, exec, s[40:41]
	s_cbranch_execnz .LBB0_897
	s_or_b64 exec, exec, s[40:41]
	s_branch .LBB0_890
